# v76 + attention item prologue: dropped the second vmcnt(0) so tile-1 K/V DMA overlaps the first tile (loop's own counted wait covers it)
# baseline (speedup 1.0000x reference)
.LBB0_529:
	s_or_b64 exec, exec, s[4:5]
	s_ashr_i32 s44, s87, 3
	s_lshl_b32 s4, s87, 7
	s_ashr_i32 s45, s44, 31
	s_sub_i32 s86, s53, s4
	s_lshl_b32 s96, s84, 23
	s_lshl_b64 s[36:37], s[44:45], 22
	s_add_u32 s4, s92, s36
	s_addc_u32 s5, s93, s37
	s_add_u32 s4, s4, s96
	s_addc_u32 s5, s5, 0
	s_add_u32 s48, s4, 0x4000000
	s_addc_u32 s49, s5, 0
	s_lshl_b32 s85, s86, 7
	s_lshl_b32 s6, s84, 2
	v_and_b32_e32 v154, 31, v153
	v_mov_b32_e32 v0, s6
	s_or_b32 s6, s85, s71
	v_or_b32_e32 v132, s6, v154
	v_ashrrev_i32_e32 v133, 31, v132
	v_readlane_b32 s8, v254, 32
	v_lshlrev_b64 v[2:3], 8, v[132:133]
	v_bfe_u32 v155, v153, 5, 1
	v_readlane_b32 s12, v254, 36
	v_readlane_b32 s13, v254, 37
	v_lshl_add_u64 v[2:3], s[4:5], 0, v[2:3]
	v_bfe_u32 v140, v153, 4, 2
	s_nop 2
	global_load_dword v6, v0, s[12:13] offset:480
	global_load_dword v7, v0, s[12:13] offset:992
	v_lshl_add_u64 v[2:3], v[2:3], 0, s[26:27]
	v_lshlrev_b32_e32 v130, 4, v155
	v_mov_b32_e32 v131, v1
	v_or_b32_e32 v0, s62, v140
	v_lshl_add_u64 v[2:3], v[2:3], 0, v[130:131]
	v_lshlrev_b32_e32 v8, 4, v153
	v_lshlrev_b32_e32 v161, 4, v0
	global_load_dwordx4 v[110:113], v[2:3], off
	global_load_dwordx4 v[106:109], v[2:3], off offset:32
	global_load_dwordx4 v[102:105], v[2:3], off offset:64
	global_load_dwordx4 v[98:101], v[2:3], off offset:96
	v_and_b32_e32 v160, 0xf0, v8
	v_lshlrev_b32_e32 v2, 8, v0
	v_and_b32_e32 v0, 0x70, v161
	v_bitop3_b32 v0, v0, v2, v160 bitop3:0xde
	v_bfe_u32 v2, v153, 2, 3
	s_mov_b32 s6, 0xffffff3
	v_bitop3_b32 v141, v2, s6, v148 bitop3:0xc8
	v_lshrrev_b32_e32 v2, 1, v153
	v_readlane_b32 s18, v254, 42
	s_cmp_lg_u32 0, -1
	v_and_b32_e32 v143, 8, v2
	v_or_b32_e32 v3, s73, v155
	v_and_b32_e32 v159, 48, v8
	v_readlane_b32 s9, v254, 33
	s_cselect_b32 s18, 0, 0
	v_or3_b32 v2, v141, v143, s72
	v_lshl_or_b32 v3, v3, 6, v159
	s_add_i32 s7, s74, 0xc000
	v_lshl_or_b32 v2, v2, 8, v3
	s_mov_b32 m0, s7
	v_lshl_add_u64 v[134:135], s[4:5], 0, v[0:1]
	s_mov_b64 s[8:9], 0x4002000
	s_add_i32 s6, s74, 0xe000
	v_mov_b32_e32 v3, v1
	global_load_lds_dwordx4 v0, s[48:49]
	v_lshl_add_u64 v[4:5], v[134:135], 0, s[8:9]
	s_mov_b32 m0, s6
	v_lshl_add_u64 v[136:137], s[4:5], 0, v[2:3]
	s_mov_b64 s[4:5], 0x8000000
	global_load_lds_dwordx4 v[4:5], off
	v_lshl_add_u64 v[2:3], v[136:137], 0, s[4:5]
	s_mov_b32 m0, s74
	s_mov_b64 s[4:5], 0x8002000
	global_load_lds_dwordx4 v[2:3], off
	v_lshl_add_u64 v[2:3], v[136:137], 0, s[4:5]
	s_add_i32 m0, s74, 0x2000
	s_mov_b64 s[4:5], 0x4004000
	global_load_lds_dwordx4 v[2:3], off
	v_lshl_add_u64 v[2:3], v[134:135], 0, s[4:5]
	s_add_i32 m0, s74, 0x10000
	s_mov_b64 s[4:5], 0x4006000
	global_load_lds_dwordx4 v[2:3], off
	v_lshl_add_u64 v[2:3], v[134:135], 0, s[4:5]
	s_add_i32 m0, s74, 0x12000
	s_mov_b64 s[4:5], 0x4008000
	global_load_lds_dwordx4 v[2:3], off
	s_waitcnt vmcnt(0) lgkmcnt(0)
	v_cmp_gt_i32_e32 vcc, 0x101, v153
	s_and_saveexec_b64 s[100:101], vcc
	v_mul_f32_e32 v252, 0x3fb8aa3b, v252
	ds_write_b32 v253, v252
	s_or_b64 exec, exec, s[100:101]
	s_waitcnt lgkmcnt(0)
	s_barrier
	v_lshl_add_u64 v[2:3], v[134:135], 0, s[4:5]
	s_add_i32 m0, s74, 0x14000
	s_mov_b64 s[4:5], 0x400a000
	global_load_lds_dwordx4 v[2:3], off
	v_lshl_add_u64 v[2:3], v[134:135], 0, s[4:5]
	s_add_i32 m0, s74, 0x16000
	s_mov_b64 s[4:5], 0x8004000
	global_load_lds_dwordx4 v[2:3], off
	v_lshl_add_u64 v[2:3], v[136:137], 0, s[4:5]
	s_add_i32 m0, s74, 0x4000
	s_mov_b64 s[4:5], 0x8006000
	global_load_lds_dwordx4 v[2:3], off
	v_lshl_add_u64 v[2:3], v[136:137], 0, s[4:5]
	s_add_i32 m0, s74, 0x6000
	v_lshlrev_b32_e32 v4, 6, v153
	global_load_lds_dwordx4 v[2:3], off
	v_lshlrev_b32_e32 v2, 3, v153
	v_and_b32_e32 v3, 0xc0, v8
	v_and_or_b32 v2, v2, 24, v3
	v_lshlrev_b32_e32 v3, 1, v153
	v_and_b32_e32 v3, 32, v3
	v_and_b32_e32 v4, 0x800, v4
	v_or3_b32 v2, v2, v3, v4
	v_lshlrev_b32_e32 v156, 8, v154
	v_lshlrev_b32_e32 v164, 4, v154
	v_and_b32_e32 v131, 63, v153
	s_nop 0
	v_mul_f32_e32 v142, 0x3fb8aa3b, v6
	v_mul_f32_e32 v133, 0x3fb8aa3b, v7
	v_add_u32_e32 v157, s18, v2
	s_mov_b64 s[4:5], -1
	s_and_b64 vcc, exec, s[28:29]
	v_and_b32_e32 v162, 0x70, v164
	v_add_u32_e32 v163, 0, v156
	v_lshlrev_b32_e32 v158, 2, v155
	v_readlane_b32 s10, v254, 34
	v_readlane_b32 s11, v254, 35
	v_readlane_b32 s14, v254, 38
	v_readlane_b32 s15, v254, 39
	v_readlane_b32 s16, v254, 40
	v_readlane_b32 s17, v254, 41
	v_readlane_b32 s19, v254, 43
	v_readlane_b32 s20, v254, 44
	v_readlane_b32 s21, v254, 45
	v_readlane_b32 s22, v254, 46
	v_readlane_b32 s23, v254, 47
	s_branch .LBB0_562
	v_bitop3_b32 v167, v130, v162, s64 bitop3:0x36
	v_add_u32_e32 v6, v163, v167
	ds_read_b128 v[2:5], v6 offset:49152
	ds_read_b128 v[6:9], v6 offset:57344
	s_movk_i32 s4, 0xa0
	v_bitop3_b32 v168, v130, v162, s4 bitop3:0x36
	v_add_u32_e32 v38, v163, v168
	s_waitcnt lgkmcnt(0)
	v_mfma_f32_32x32x16_bf16 v[18:33], v[2:5], v[110:113], 0
	ds_read_b128 v[34:37], v38 offset:49152
	ds_read_b128 v[38:41], v38 offset:57344
	s_movk_i32 s4, 0xc0
	v_bitop3_b32 v169, v130, v162, s4 bitop3:0x36
	v_add_u32_e32 v42, v163, v169
	s_movk_i32 s4, 0xe0
	v_bitop3_b32 v170, v130, v162, s4 bitop3:0x36
	v_add_u32_e32 v46, v163, v170
	v_mfma_f32_32x32x16_bf16 v[2:17], v[6:9], v[110:113], 0
	s_mov_b64 s[4:5], 0x400c000
	s_mov_b32 m0, s7
	v_sub_u32_e32 v166, v158, v132
	s_waitcnt lgkmcnt(1)
	v_mfma_f32_32x32x16_bf16 v[18:33], v[34:37], v[106:109], v[18:33]
	ds_read_b128 v[34:37], v42 offset:49152
	ds_read_b128 v[42:45], v42 offset:57344
	s_waitcnt lgkmcnt(2)
	v_mfma_f32_32x32x16_bf16 v[2:17], v[38:41], v[106:109], v[2:17]
	ds_read_b128 v[38:41], v46 offset:49152
	ds_read_b128 v[46:49], v46 offset:57344
	s_waitcnt vmcnt(4) lgkmcnt(0)
	s_barrier
	s_waitcnt lgkmcnt(3)
	v_mfma_f32_32x32x16_bf16 v[18:33], v[34:37], v[102:105], v[18:33]
	v_lshl_add_u64 v[34:35], v[134:135], 0, s[4:5]
	s_mov_b64 s[4:5], 0x400e000
	global_load_lds_dwordx4 v[34:35], off
	v_lshl_add_u64 v[34:35], v[134:135], 0, s[4:5]
	s_mov_b32 m0, s6
	s_mov_b64 s[4:5], 0x8008000
	global_load_lds_dwordx4 v[34:35], off
	v_lshl_add_u64 v[34:35], v[136:137], 0, s[4:5]
	s_mov_b32 m0, s81
	s_mov_b64 s[4:5], 0x800a000
	global_load_lds_dwordx4 v[34:35], off
	v_lshl_add_u64 v[34:35], v[136:137], 0, s[4:5]
	s_mov_b32 m0, s82
	s_waitcnt lgkmcnt(0)
	v_mfma_f32_32x32x16_bf16 v[2:17], v[42:45], v[102:105], v[2:17]
	global_load_lds_dwordx4 v[34:35], off
	s_add_i32 s4, s85, 0xd9
	s_cmpk_gt_u32 s4, 0x172
	v_mfma_f32_32x32x16_bf16 v[18:33], v[38:41], v[98:101], v[18:33]
	v_mfma_f32_32x32x16_bf16 v[2:17], v[46:49], v[98:101], v[2:17]
	s_cbranch_scc1 .LBB0_532
	v_mov_b32_e32 v58, v166
	s_add_i32 s4, 0, 0x18800
	v_add_u32_e32 v36, 1, v58
	v_med3_i32 v37, v36, s65, v146
	v_med3_i32 v36, v36, s69, v147
	v_lshl_add_u32 v38, v36, 2, s4
	v_add_u32_e32 v36, 2, v58
	v_med3_i32 v39, v36, s65, v146
	v_med3_i32 v36, v36, s69, v147
	v_lshl_add_u32 v40, v36, 2, s4
	v_add_u32_e32 v36, 3, v58
	v_med3_i32 v34, v58, s65, v146
	v_med3_i32 v35, v58, s69, v147
	v_med3_i32 v41, v36, s65, v146
	v_med3_i32 v36, v36, s69, v147
	v_lshl_add_u32 v34, v34, 2, s4
	v_lshl_add_u32 v35, v35, 2, s4
	v_lshl_add_u32 v37, v37, 2, s4
	v_lshl_add_u32 v39, v39, 2, s4
	v_lshl_add_u32 v41, v41, 2, s4
	v_lshl_add_u32 v42, v36, 2, s4
	ds_read_b32 v34, v34 offset:512
	ds_read_b32 v36, v35 offset:640
	ds_read_b32 v35, v37 offset:512
	ds_read_b32 v37, v38 offset:640
	ds_read_b32 v38, v39 offset:512
	ds_read_b32 v40, v40 offset:640
	ds_read_b32 v39, v41 offset:512
	ds_read_b32 v41, v42 offset:640
	v_add_u32_e32 v42, 8, v58
	v_med3_i32 v43, v42, s65, v146
	v_med3_i32 v42, v42, s69, v147
	v_lshl_add_u32 v44, v42, 2, s4
	v_add_u32_e32 v42, 9, v58
	v_med3_i32 v45, v42, s65, v146
	v_med3_i32 v42, v42, s69, v147
	v_lshl_add_u32 v46, v42, 2, s4
	v_add_u32_e32 v42, 10, v58
	v_med3_i32 v47, v42, s65, v146
	v_med3_i32 v42, v42, s69, v147
	v_lshl_add_u32 v48, v42, 2, s4
	v_add_u32_e32 v42, 11, v58
	v_med3_i32 v49, v42, s65, v146
	v_med3_i32 v42, v42, s69, v147
	v_lshl_add_u32 v43, v43, 2, s4
	v_lshl_add_u32 v45, v45, 2, s4
	v_lshl_add_u32 v47, v47, 2, s4
	v_lshl_add_u32 v49, v49, 2, s4
	v_lshl_add_u32 v50, v42, 2, s4
	ds_read_b32 v42, v43 offset:512
	ds_read_b32 v44, v44 offset:640
	ds_read_b32 v43, v45 offset:512
	ds_read_b32 v45, v46 offset:640
	ds_read_b32 v46, v47 offset:512
	ds_read_b32 v48, v48 offset:640
	ds_read_b32 v47, v49 offset:512
	ds_read_b32 v49, v50 offset:640
	v_add_u32_e32 v50, 16, v58
	v_med3_i32 v51, v50, s65, v146
	v_med3_i32 v50, v50, s69, v147
	v_lshl_add_u32 v52, v50, 2, s4
	v_add_u32_e32 v50, 17, v58
	v_med3_i32 v53, v50, s65, v146
	v_med3_i32 v50, v50, s69, v147
	v_lshl_add_u32 v54, v50, 2, s4
	v_add_u32_e32 v50, 18, v58
	v_med3_i32 v55, v50, s65, v146
	v_med3_i32 v50, v50, s69, v147
	v_lshl_add_u32 v56, v50, 2, s4
	v_add_u32_e32 v50, 19, v58
	v_add_u32_e32 v61, 25, v58
	v_med3_i32 v57, v50, s65, v146
	v_med3_i32 v50, v50, s69, v147
	v_med3_i32 v62, v61, s65, v146
	v_lshl_add_u32 v51, v51, 2, s4
	v_lshl_add_u32 v53, v53, 2, s4
	v_lshl_add_u32 v55, v55, 2, s4
	v_lshl_add_u32 v57, v57, 2, s4
	v_lshl_add_u32 v59, v50, 2, s4
	v_lshl_add_u32 v64, v62, 2, s4
	v_add_u32_e32 v62, 26, v58
	ds_read_b32 v50, v51 offset:512
	ds_read_b32 v52, v52 offset:640
	ds_read_b32 v51, v53 offset:512
	ds_read_b32 v53, v54 offset:640
	ds_read_b32 v54, v55 offset:512
	ds_read_b32 v56, v56 offset:640
	ds_read_b32 v55, v57 offset:512
	ds_read_b32 v57, v59 offset:640
	v_add_u32_e32 v59, 24, v58
	v_med3_i32 v63, v62, s65, v146
	v_med3_i32 v62, v62, s69, v147
	v_add_u32_e32 v58, 27, v58
	v_med3_i32 v60, v59, s65, v146
	v_med3_i32 v59, v59, s69, v147
	v_med3_i32 v61, v61, s69, v147
	v_lshl_add_u32 v66, v62, 2, s4
	v_med3_i32 v62, v58, s65, v146
	v_lshl_add_u32 v60, v60, 2, s4
	v_lshl_add_u32 v59, v59, 2, s4
	v_lshl_add_u32 v61, v61, 2, s4
	v_lshl_add_u32 v63, v63, 2, s4
	v_med3_i32 v58, v58, s69, v147
	v_lshl_add_u32 v65, v62, 2, s4
	v_lshl_add_u32 v67, v58, 2, s4
	ds_read_b32 v58, v60 offset:512
	ds_read_b32 v60, v59 offset:640
	ds_read_b32 v62, v63 offset:512
	ds_read_b32 v63, v65 offset:512
	ds_read_b32 v59, v64 offset:512
	ds_read_b32 v65, v67 offset:640
	ds_read_b32 v64, v66 offset:640
	ds_read_b32 v61, v61 offset:640
	s_waitcnt lgkmcnt(0)
	v_pk_add_f32 v[32:33], v[32:33], v[62:63]
	v_pk_add_f32 v[30:31], v[30:31], v[58:59]
	v_pk_add_f32 v[28:29], v[28:29], v[54:55]
	v_pk_add_f32 v[26:27], v[26:27], v[50:51]
	v_pk_add_f32 v[24:25], v[24:25], v[46:47]
	v_pk_add_f32 v[22:23], v[22:23], v[42:43]
	v_pk_add_f32 v[20:21], v[20:21], v[38:39]
	v_pk_add_f32 v[18:19], v[18:19], v[34:35]
	v_pk_add_f32 v[16:17], v[16:17], v[64:65]
	v_pk_add_f32 v[14:15], v[14:15], v[60:61]
	v_pk_add_f32 v[12:13], v[12:13], v[56:57]
	v_pk_add_f32 v[10:11], v[10:11], v[52:53]
	v_pk_add_f32 v[8:9], v[8:9], v[48:49]
	v_pk_add_f32 v[6:7], v[6:7], v[44:45]
	v_pk_add_f32 v[4:5], v[4:5], v[40:41]
	v_pk_add_f32 v[2:3], v[2:3], v[36:37]

.LBB0_689:
	s_or_b64 exec, exec, s[4:5]
	s_ashr_i32 s40, s82, 3
	s_lshl_b32 s4, s82, 6
	s_ashr_i32 s41, s40, 31
	s_sub_i32 s81, s48, s4
	s_lshl_b32 s83, s79, 23
	s_lshl_b64 s[10:11], s[40:41], 21
	s_add_u32 s4, s92, s10
	s_addc_u32 s5, s93, s11
	s_add_u32 s4, s4, s83
	s_addc_u32 s5, s5, 0
	s_add_u32 s44, s4, 0x4000000
	s_addc_u32 s45, s5, 0
	s_lshl_b32 s80, s81, 7
	s_lshl_b32 s6, s79, 2
	v_and_b32_e32 v154, 31, v153
	v_mov_b32_e32 v0, s6
	s_or_b32 s6, s80, s67
	v_or_b32_e32 v132, s6, v154
	v_ashrrev_i32_e32 v133, 31, v132
	v_readlane_b32 s12, v254, 32
	v_lshlrev_b64 v[2:3], 8, v[132:133]
	v_bfe_u32 v155, v153, 5, 1
	v_readlane_b32 s16, v254, 36
	v_readlane_b32 s17, v254, 37
	v_lshl_add_u64 v[2:3], s[4:5], 0, v[2:3]
	v_bfe_u32 v140, v153, 4, 2
	s_nop 2
	global_load_dword v6, v0, s[16:17] offset:480
	global_load_dword v7, v0, s[16:17] offset:992
	v_lshl_add_u64 v[2:3], v[2:3], 0, s[28:29]
	v_lshlrev_b32_e32 v130, 4, v155
	v_mov_b32_e32 v131, v1
	v_or_b32_e32 v0, s49, v140
	v_lshl_add_u64 v[2:3], v[2:3], 0, v[130:131]
	v_lshlrev_b32_e32 v8, 4, v153
	v_lshlrev_b32_e32 v161, 4, v0
	global_load_dwordx4 v[110:113], v[2:3], off
	global_load_dwordx4 v[106:109], v[2:3], off offset:32
	global_load_dwordx4 v[102:105], v[2:3], off offset:64
	global_load_dwordx4 v[98:101], v[2:3], off offset:96
	v_and_b32_e32 v160, 0xf0, v8
	v_lshlrev_b32_e32 v2, 8, v0
	v_and_b32_e32 v0, 0x70, v161
	v_bitop3_b32 v0, v0, v2, v160 bitop3:0xde
	v_bfe_u32 v2, v153, 2, 3
	s_mov_b32 s6, 0xffffff3
	v_bitop3_b32 v141, v2, s6, v148 bitop3:0xc8
	v_lshrrev_b32_e32 v2, 1, v153
	v_readlane_b32 s18, v254, 38
	s_cmp_lg_u32 0, -1
	v_and_b32_e32 v143, 8, v2
	v_or_b32_e32 v3, s69, v155
	v_and_b32_e32 v159, 48, v8
	s_cselect_b32 s18, 0, 0
	v_or3_b32 v2, v141, v143, s68
	v_lshl_or_b32 v3, v3, 6, v159
	s_add_i32 s7, s70, 0xc000
	v_lshl_or_b32 v2, v2, 8, v3
	s_mov_b32 m0, s7
	v_lshl_add_u64 v[134:135], s[4:5], 0, v[0:1]
	s_mov_b64 s[8:9], 0x4002000
	s_add_i32 s6, s70, 0xe000
	v_mov_b32_e32 v3, v1
	global_load_lds_dwordx4 v0, s[44:45]
	v_lshl_add_u64 v[4:5], v[134:135], 0, s[8:9]
	s_mov_b32 m0, s6
	v_lshl_add_u64 v[136:137], s[4:5], 0, v[2:3]
	s_mov_b64 s[4:5], 0x8000000
	global_load_lds_dwordx4 v[4:5], off
	v_lshl_add_u64 v[2:3], v[136:137], 0, s[4:5]
	s_mov_b32 m0, s70
	s_mov_b64 s[4:5], 0x8002000
	global_load_lds_dwordx4 v[2:3], off
	v_lshl_add_u64 v[2:3], v[136:137], 0, s[4:5]
	s_add_i32 m0, s70, 0x2000
	s_mov_b64 s[4:5], 0x4004000
	global_load_lds_dwordx4 v[2:3], off
	v_lshl_add_u64 v[2:3], v[134:135], 0, s[4:5]
	s_add_i32 m0, s70, 0x10000
	s_mov_b64 s[4:5], 0x4006000
	global_load_lds_dwordx4 v[2:3], off
	v_lshl_add_u64 v[2:3], v[134:135], 0, s[4:5]
	s_add_i32 m0, s70, 0x12000
	s_mov_b64 s[4:5], 0x4008000
	global_load_lds_dwordx4 v[2:3], off
	s_waitcnt vmcnt(0) lgkmcnt(0)
	v_cmp_gt_i32_e32 vcc, 0x101, v153
	s_and_saveexec_b64 s[100:101], vcc
	v_mul_f32_e32 v252, 0x3fb8aa3b, v252
	ds_write_b32 v253, v252
	s_or_b64 exec, exec, s[100:101]
	s_waitcnt lgkmcnt(0)
	s_barrier
	v_lshl_add_u64 v[2:3], v[134:135], 0, s[4:5]
	s_add_i32 m0, s70, 0x14000
	s_mov_b64 s[4:5], 0x400a000
	global_load_lds_dwordx4 v[2:3], off
	v_lshl_add_u64 v[2:3], v[134:135], 0, s[4:5]
	s_add_i32 m0, s70, 0x16000
	s_mov_b64 s[4:5], 0x8004000
	global_load_lds_dwordx4 v[2:3], off
	v_lshl_add_u64 v[2:3], v[136:137], 0, s[4:5]
	s_add_i32 m0, s70, 0x4000
	s_mov_b64 s[4:5], 0x8006000
	global_load_lds_dwordx4 v[2:3], off
	v_lshl_add_u64 v[2:3], v[136:137], 0, s[4:5]
	s_add_i32 m0, s70, 0x6000
	v_lshlrev_b32_e32 v4, 6, v153
	global_load_lds_dwordx4 v[2:3], off
	v_lshlrev_b32_e32 v2, 3, v153
	v_and_b32_e32 v3, 0xc0, v8
	v_and_or_b32 v2, v2, 24, v3
	v_lshlrev_b32_e32 v3, 1, v153
	v_and_b32_e32 v3, 32, v3
	v_and_b32_e32 v4, 0x800, v4
	v_or3_b32 v2, v2, v3, v4
	v_lshlrev_b32_e32 v156, 8, v154
	v_lshlrev_b32_e32 v164, 4, v154
	v_and_b32_e32 v131, 63, v153
	s_nop 0
	v_mul_f32_e32 v142, 0x3fb8aa3b, v6
	v_mul_f32_e32 v133, 0x3fb8aa3b, v7
	v_add_u32_e32 v157, s18, v2
	s_mov_b64 s[4:5], -1
	s_and_b64 vcc, exec, s[36:37]
	v_and_b32_e32 v162, 0x70, v164
	v_add_u32_e32 v163, 0, v156
	v_lshlrev_b32_e32 v158, 2, v155
	v_readlane_b32 s13, v254, 33
	v_readlane_b32 s14, v254, 34
	v_readlane_b32 s15, v254, 35
	v_readlane_b32 s19, v254, 39
	v_readlane_b32 s20, v254, 40
	v_readlane_b32 s21, v254, 41
	v_readlane_b32 s22, v254, 42
	v_readlane_b32 s23, v254, 43
	v_readlane_b32 s24, v254, 44
	v_readlane_b32 s25, v254, 45
	v_readlane_b32 s26, v254, 46
	v_readlane_b32 s27, v254, 47
	s_branch .LBB0_722
	v_bitop3_b32 v167, v130, v162, s51 bitop3:0x36
	v_add_u32_e32 v6, v163, v167
	ds_read_b128 v[2:5], v6 offset:49152
	ds_read_b128 v[6:9], v6 offset:57344
	s_movk_i32 s4, 0xa0
	v_bitop3_b32 v168, v130, v162, s4 bitop3:0x36
	v_add_u32_e32 v38, v163, v168
	s_waitcnt lgkmcnt(0)
	v_mfma_f32_32x32x16_bf16 v[18:33], v[2:5], v[110:113], 0
	ds_read_b128 v[34:37], v38 offset:49152
	ds_read_b128 v[38:41], v38 offset:57344
	s_movk_i32 s4, 0xc0
	v_bitop3_b32 v169, v130, v162, s4 bitop3:0x36
	v_add_u32_e32 v42, v163, v169
	s_movk_i32 s4, 0xe0
	v_bitop3_b32 v170, v130, v162, s4 bitop3:0x36
	v_add_u32_e32 v46, v163, v170
	v_mfma_f32_32x32x16_bf16 v[2:17], v[6:9], v[110:113], 0
	s_mov_b64 s[4:5], 0x400c000
	s_mov_b32 m0, s7
	v_sub_u32_e32 v166, v158, v132
	s_waitcnt lgkmcnt(1)
	v_mfma_f32_32x32x16_bf16 v[18:33], v[34:37], v[106:109], v[18:33]
	ds_read_b128 v[34:37], v42 offset:49152
	ds_read_b128 v[42:45], v42 offset:57344
	s_waitcnt lgkmcnt(2)
	v_mfma_f32_32x32x16_bf16 v[2:17], v[38:41], v[106:109], v[2:17]
	ds_read_b128 v[38:41], v46 offset:49152
	ds_read_b128 v[46:49], v46 offset:57344
	s_waitcnt vmcnt(4) lgkmcnt(0)
	s_barrier
	s_waitcnt lgkmcnt(3)
	v_mfma_f32_32x32x16_bf16 v[18:33], v[34:37], v[102:105], v[18:33]
	v_lshl_add_u64 v[34:35], v[134:135], 0, s[4:5]
	s_mov_b64 s[4:5], 0x400e000
	global_load_lds_dwordx4 v[34:35], off
	v_lshl_add_u64 v[34:35], v[134:135], 0, s[4:5]
	s_mov_b32 m0, s6
	s_mov_b64 s[4:5], 0x8008000
	global_load_lds_dwordx4 v[34:35], off
	v_lshl_add_u64 v[34:35], v[136:137], 0, s[4:5]
	s_mov_b32 m0, s76
	s_mov_b64 s[4:5], 0x800a000
	global_load_lds_dwordx4 v[34:35], off
	v_lshl_add_u64 v[34:35], v[136:137], 0, s[4:5]
	s_mov_b32 m0, s77
	s_waitcnt lgkmcnt(0)
	v_mfma_f32_32x32x16_bf16 v[2:17], v[42:45], v[102:105], v[2:17]
	global_load_lds_dwordx4 v[34:35], off
	s_add_i32 s4, s80, 0xd9
	s_cmpk_gt_u32 s4, 0x172
	v_mfma_f32_32x32x16_bf16 v[18:33], v[38:41], v[98:101], v[18:33]
	v_mfma_f32_32x32x16_bf16 v[2:17], v[46:49], v[98:101], v[2:17]
	s_cbranch_scc1 .LBB0_692
	v_mov_b32_e32 v58, v166
	s_add_i32 s4, 0, 0x18800
	v_add_u32_e32 v36, 1, v58
	v_med3_i32 v37, v36, s53, v146
	v_med3_i32 v36, v36, s65, v147
	v_lshl_add_u32 v38, v36, 2, s4
	v_add_u32_e32 v36, 2, v58
	v_med3_i32 v39, v36, s53, v146
	v_med3_i32 v36, v36, s65, v147
	v_lshl_add_u32 v40, v36, 2, s4
	v_add_u32_e32 v36, 3, v58
	v_med3_i32 v34, v58, s53, v146
	v_med3_i32 v35, v58, s65, v147
	v_med3_i32 v41, v36, s53, v146
	v_med3_i32 v36, v36, s65, v147
	v_lshl_add_u32 v34, v34, 2, s4
	v_lshl_add_u32 v35, v35, 2, s4
	v_lshl_add_u32 v37, v37, 2, s4
	v_lshl_add_u32 v39, v39, 2, s4
	v_lshl_add_u32 v41, v41, 2, s4
	v_lshl_add_u32 v42, v36, 2, s4
	ds_read_b32 v34, v34 offset:512
	ds_read_b32 v36, v35 offset:640
	ds_read_b32 v35, v37 offset:512
	ds_read_b32 v37, v38 offset:640
	ds_read_b32 v38, v39 offset:512
	ds_read_b32 v40, v40 offset:640
	ds_read_b32 v39, v41 offset:512
	ds_read_b32 v41, v42 offset:640
	v_add_u32_e32 v42, 8, v58
	v_med3_i32 v43, v42, s53, v146
	v_med3_i32 v42, v42, s65, v147
	v_lshl_add_u32 v44, v42, 2, s4
	v_add_u32_e32 v42, 9, v58
	v_med3_i32 v45, v42, s53, v146
	v_med3_i32 v42, v42, s65, v147
	v_lshl_add_u32 v46, v42, 2, s4
	v_add_u32_e32 v42, 10, v58
	v_med3_i32 v47, v42, s53, v146
	v_med3_i32 v42, v42, s65, v147
	v_lshl_add_u32 v48, v42, 2, s4
	v_add_u32_e32 v42, 11, v58
	v_med3_i32 v49, v42, s53, v146
	v_med3_i32 v42, v42, s65, v147
	v_lshl_add_u32 v43, v43, 2, s4
	v_lshl_add_u32 v45, v45, 2, s4
	v_lshl_add_u32 v47, v47, 2, s4
	v_lshl_add_u32 v49, v49, 2, s4
	v_lshl_add_u32 v50, v42, 2, s4
	ds_read_b32 v42, v43 offset:512
	ds_read_b32 v44, v44 offset:640
	ds_read_b32 v43, v45 offset:512
	ds_read_b32 v45, v46 offset:640
	ds_read_b32 v46, v47 offset:512
	ds_read_b32 v48, v48 offset:640
	ds_read_b32 v47, v49 offset:512
	ds_read_b32 v49, v50 offset:640
	v_add_u32_e32 v50, 16, v58
	v_med3_i32 v51, v50, s53, v146
	v_med3_i32 v50, v50, s65, v147
	v_lshl_add_u32 v52, v50, 2, s4
	v_add_u32_e32 v50, 17, v58
	v_med3_i32 v53, v50, s53, v146
	v_med3_i32 v50, v50, s65, v147
	v_lshl_add_u32 v54, v50, 2, s4
	v_add_u32_e32 v50, 18, v58
	v_med3_i32 v55, v50, s53, v146
	v_med3_i32 v50, v50, s65, v147
	v_lshl_add_u32 v56, v50, 2, s4
	v_add_u32_e32 v50, 19, v58
	v_add_u32_e32 v61, 25, v58
	v_med3_i32 v57, v50, s53, v146
	v_med3_i32 v50, v50, s65, v147
	v_med3_i32 v62, v61, s53, v146
	v_lshl_add_u32 v51, v51, 2, s4
	v_lshl_add_u32 v53, v53, 2, s4
	v_lshl_add_u32 v55, v55, 2, s4
	v_lshl_add_u32 v57, v57, 2, s4
	v_lshl_add_u32 v59, v50, 2, s4
	v_lshl_add_u32 v64, v62, 2, s4
	v_add_u32_e32 v62, 26, v58
	ds_read_b32 v50, v51 offset:512
	ds_read_b32 v52, v52 offset:640
	ds_read_b32 v51, v53 offset:512
	ds_read_b32 v53, v54 offset:640
	ds_read_b32 v54, v55 offset:512
	ds_read_b32 v56, v56 offset:640
	ds_read_b32 v55, v57 offset:512
	ds_read_b32 v57, v59 offset:640
	v_add_u32_e32 v59, 24, v58
	v_med3_i32 v63, v62, s53, v146
	v_med3_i32 v62, v62, s65, v147
	v_add_u32_e32 v58, 27, v58
	v_med3_i32 v60, v59, s53, v146
	v_med3_i32 v59, v59, s65, v147
	v_med3_i32 v61, v61, s65, v147
	v_lshl_add_u32 v66, v62, 2, s4
	v_med3_i32 v62, v58, s53, v146
	v_lshl_add_u32 v60, v60, 2, s4
	v_lshl_add_u32 v59, v59, 2, s4
	v_lshl_add_u32 v61, v61, 2, s4
	v_lshl_add_u32 v63, v63, 2, s4
	v_med3_i32 v58, v58, s65, v147
	v_lshl_add_u32 v65, v62, 2, s4
	v_lshl_add_u32 v67, v58, 2, s4
	ds_read_b32 v58, v60 offset:512
	ds_read_b32 v60, v59 offset:640
	ds_read_b32 v62, v63 offset:512
	ds_read_b32 v63, v65 offset:512
	ds_read_b32 v59, v64 offset:512
	ds_read_b32 v65, v67 offset:640
	ds_read_b32 v64, v66 offset:640
	ds_read_b32 v61, v61 offset:640
	s_waitcnt lgkmcnt(0)
	v_pk_add_f32 v[32:33], v[32:33], v[62:63]
	v_pk_add_f32 v[30:31], v[30:31], v[58:59]
	v_pk_add_f32 v[28:29], v[28:29], v[54:55]
	v_pk_add_f32 v[26:27], v[26:27], v[50:51]
	v_pk_add_f32 v[24:25], v[24:25], v[46:47]
	v_pk_add_f32 v[22:23], v[22:23], v[42:43]
	v_pk_add_f32 v[20:21], v[20:21], v[38:39]
	v_pk_add_f32 v[18:19], v[18:19], v[34:35]
	v_pk_add_f32 v[16:17], v[16:17], v[64:65]
	v_pk_add_f32 v[14:15], v[14:15], v[60:61]
	v_pk_add_f32 v[12:13], v[12:13], v[56:57]
	v_pk_add_f32 v[10:11], v[10:11], v[52:53]
	v_pk_add_f32 v[8:9], v[8:9], v[48:49]
	v_pk_add_f32 v[6:7], v[6:7], v[44:45]
	v_pk_add_f32 v[4:5], v[4:5], v[40:41]
	v_pk_add_f32 v[2:3], v[2:3], v[36:37]
